# NSA far-tile loop: all 8 K/V tile loads in flight together instead of V loads serialized one by one
# speedup vs baseline: 1.0616x; 1.0140x over previous
; DI int otid() { int z; asm volatile("s_mov_b32 %0, 0" : "=s"(z)); return (int)threadIdx.x + z; }
;   DI float aux(int key) const { return (cuml[key] + cpre[key >> 7]) * LOG2E; }
;           DI float aux(int key) const { int n = key < 511 ? key : 510; return __int_as_float(pos[16 * n + 31]); }
;   DI float aux(int key) const { return __int_as_float(pos[key]); }
;   DI float aux(int key) const { return __int_as_float(pos[key]); }
; template <int DK, bool PV, bool PF, class Ctx>
; DI void attn_run(const bf16x8 (&qf)[DK / 16], f32x16 (&o)[4], float& m, float& l, const bf16* K1, int ldk1,
;                  const bf16* K2, int ldk2, const bf16* Vt, int ldv, int first, Ctx& ctx, char* smem) {
;     ...
;   auto ldk = [&](int i, int key0) -> uint4 {
;     int c = otid() + 256 * i;
;     int row = c / CPR, cc = c % CPR;
;     const bf16* src;
;     if (DK == 128 || cc < 16) src = K1 + (size_t)(key0 + row) * ldk1 + cc * 8;
;     else src = K2 + (size_t)(key0 + row) * ldk2 + (cc - 16) * 8;
;     return *(const uint4*)src;
;   };
;   auto stk = [&](int i, const uint4& v) {
;     int c = tid + 256 * i;
;     int row = c / CPR, cc = c % CPR;
;     *(uint4*)(Ks + row * (DK + 8) + cc * 8) = v;
;   };
;   auto gload = [&](int key0) {
;     rk0 = ldk(0, key0); rk1 = ldk(1, key0); rk2 = ldk(2, key0); rk3 = ldk(3, key0);
;     if (NKC > 4) { rk4 = ldk(4, key0); rk5 = ldk(5, key0); }
;     const int tl = otid();
; #pragma unroll
;     for (int i = 0; i < 4; ++i) {
;       int c = tl + 256 * i;
;       int d = c >> 3, cc = c & 7;
;       rv[i] = *(const uint4*)(Vt + (size_t)d * ldv + key0 + cc * 8);
;     }
;     raux = (tid < 64) ? ctx.aux(key0 + tid) : 0.f;
;   };
;   auto sstore = [&]() {
;     stk(0, rk0); stk(1, rk1); stk(2, rk2); stk(3, rk3);
;     if (NKC > 4) { stk(4, rk4); stk(5, rk5); }
; #pragma unroll
;     for (int i = 0; i < 4; ++i) {
;       int c = tid + 256 * i;
;       int d = c >> 3, cc = c & 7;
;       uint2* dst = (uint2*)(Vs + d * 68 + cc * 8);
;       dst[0] = make_uint2(rv[i].x, rv[i].y);
;       dst[1] = make_uint2(rv[i].z, rv[i].w);
;     }
;     if (tid < 64) ((float*)(smem + AT_AUX))[tid] = raux;
;   };
;   if (PF) gload(tcur * 64);
;   while (tcur >= 0) {
;     __syncthreads();
;     if (!PF) gload(tcur * 64);
;     sstore();
;     __syncthreads();
.LBB0_762:
	s_waitcnt lgkmcnt(0)
	s_barrier
	s_mov_b32 s6, 0
	s_lshl_b32 s64, s26, 6
	v_add_u32_e32 v0, s6, v189
	v_ashrrev_i32_e32 v2, 31, v0
	v_lshrrev_b32_e32 v2, 28, v2
	v_add_u32_e32 v2, v0, v2
	v_ashrrev_i32_e32 v3, 4, v2
	v_and_b32_e32 v2, 0x1ffffff0, v2
	v_sub_u32_e32 v0, v0, v2
	v_add_u32_e32 v2, s64, v3
	v_mov_b64_e32 v[88:89], s[42:43]
	v_lshlrev_b32_e32 v4, 3, v0
	v_mad_i64_i32 v[2:3], s[6:7], v2, s67, v[88:89]
	v_ashrrev_i32_e32 v5, 31, v4
	v_lshl_add_u64 v[2:3], v[4:5], 1, v[2:3]
	global_load_dwordx4 v[2:5], v[2:3], off
	s_mov_b32 s6, 0
	s_nop 0
	v_add_u32_e32 v0, s6, v208
	v_ashrrev_i32_e32 v80, 31, v0
	v_lshrrev_b32_e32 v80, 28, v80
	v_add_u32_e32 v80, v0, v80
	v_ashrrev_i32_e32 v81, 4, v80
	v_and_b32_e32 v80, 0x1ffffff0, v80
	v_sub_u32_e32 v0, v0, v80
	v_add_u32_e32 v80, s64, v81
	v_lshlrev_b32_e32 v82, 3, v0
	v_mad_i64_i32 v[80:81], s[6:7], v80, s67, v[88:89]
	v_ashrrev_i32_e32 v83, 31, v82
	v_lshl_add_u64 v[80:81], v[82:83], 1, v[80:81]
	global_load_dwordx4 v[80:83], v[80:81], off
	s_mov_b32 s6, 0
	s_nop 0
	v_add_u32_e32 v0, s6, v209
	v_ashrrev_i32_e32 v84, 31, v0
	v_lshrrev_b32_e32 v84, 28, v84
	v_add_u32_e32 v84, v0, v84
	v_ashrrev_i32_e32 v85, 4, v84
	v_and_b32_e32 v84, 0x1ffffff0, v84
	v_sub_u32_e32 v0, v0, v84
	v_add_u32_e32 v84, s64, v85
	v_lshlrev_b32_e32 v86, 3, v0
	v_mad_i64_i32 v[84:85], s[6:7], v84, s67, v[88:89]
	v_ashrrev_i32_e32 v87, 31, v86
	v_lshl_add_u64 v[84:85], v[86:87], 1, v[84:85]
	global_load_dwordx4 v[84:87], v[84:85], off
	s_mov_b32 s6, 0
	s_nop 0
	v_add_u32_e32 v0, s6, v210
	v_ashrrev_i32_e32 v90, 31, v0
	v_lshrrev_b32_e32 v90, 28, v90
	v_add_u32_e32 v90, v0, v90
	v_ashrrev_i32_e32 v91, 4, v90
	v_and_b32_e32 v90, 0x1ffffff0, v90
	v_sub_u32_e32 v0, v0, v90
	v_add_u32_e32 v90, s64, v91
	v_mad_i64_i32 v[88:89], s[6:7], v90, s67, v[88:89]
	v_lshlrev_b32_e32 v90, 3, v0
	v_ashrrev_i32_e32 v91, 31, v90
	v_lshl_add_u64 v[88:89], v[90:91], 1, v[88:89]
	global_load_dwordx4 v[88:91], v[88:89], off
	s_mov_b32 s6, 0
	v_add_u32_e32 v98, s6, v189
	v_ashrrev_i32_e32 v92, 3, v98
	v_ashrrev_i32_e32 v93, 31, v92
	v_lshlrev_b64 v[92:93], 14, v[92:93]
	v_lshl_add_u64 v[92:93], s[0:1], 0, v[92:93]
	s_lshl_b64 s[6:7], s[64:65], 1
	v_lshlrev_b32_e32 v0, 4, v98
	v_lshl_add_u64 v[92:93], v[92:93], 0, s[6:7]
	v_and_b32_e32 v0, 0x70, v0
	v_lshl_add_u64 v[92:93], v[92:93], 0, v[0:1]
	global_load_dwordx4 v[100:103], v[92:93], off
	v_add_u32_e32 v94, 0x100, v98
	v_ashrrev_i32_e32 v94, 3, v94
	v_ashrrev_i32_e32 v95, 31, v94
	v_lshlrev_b64 v[94:95], 14, v[94:95]
	v_lshl_add_u64 v[94:95], s[0:1], 0, v[94:95]
	v_lshl_add_u64 v[94:95], v[94:95], 0, s[6:7]
	v_lshl_add_u64 v[94:95], v[94:95], 0, v[0:1]
	v_add_u32_e32 v96, 0x200, v98
	v_ashrrev_i32_e32 v96, 3, v96
	v_ashrrev_i32_e32 v97, 31, v96
	v_lshlrev_b64 v[96:97], 14, v[96:97]
	v_lshl_add_u64 v[96:97], s[0:1], 0, v[96:97]
	v_lshl_add_u64 v[96:97], v[96:97], 0, s[6:7]
	v_lshl_add_u64 v[96:97], v[96:97], 0, v[0:1]
	v_add_u32_e32 v98, 0x300, v98
	v_ashrrev_i32_e32 v98, 3, v98
	v_ashrrev_i32_e32 v99, 31, v98
	v_lshlrev_b64 v[98:99], 14, v[98:99]
	v_lshl_add_u64 v[98:99], s[0:1], 0, v[98:99]
	v_lshl_add_u64 v[98:99], v[98:99], 0, s[6:7]
	v_lshl_add_u64 v[98:99], v[98:99], 0, v[0:1]
	global_load_dwordx4 v[104:107], v[94:95], off
	global_load_dwordx4 v[108:111], v[96:97], off
	s_waitcnt vmcnt(6)
	ds_write_b128 v8, v[2:5]
	global_load_dwordx4 v[2:5], v[98:99], off
	s_waitcnt vmcnt(6)
	ds_write_b128 v9, v[80:83]
	s_waitcnt vmcnt(5)
	ds_write_b128 v10, v[84:87]
	s_waitcnt vmcnt(4)
	ds_write_b128 v11, v[88:91]
	s_waitcnt vmcnt(3)
	ds_write2_b64 v12, v[100:101], v[102:103] offset1:1
	s_waitcnt vmcnt(2)
	ds_write2_b64 v13, v[104:105], v[106:107] offset1:1
	s_waitcnt vmcnt(1)
	ds_write2_b64 v14, v[108:109], v[110:111] offset1:1
	s_waitcnt vmcnt(0)
	ds_write2_b64 v15, v[2:3], v[4:5] offset1:1
	s_and_saveexec_b64 s[6:7], s[10:11]
	ds_write_b32 v7, v1 offset:43008
	s_or_b64 exec, exec, s[6:7]
	s_cmpk_gt_u32 s26, 0x7e
	s_mov_b32 s6, -1
	s_waitcnt lgkmcnt(0)
	s_barrier
	s_cbranch_scc1 .LBB0_772
	s_add_i32 s27, s64, 0x7f
	s_mov_b32 s36, s26
	s_branch .LBB0_767
